# LDS bank-conflict swizzle (strategy 6) extended to P10's transposed-V tile: chunk index XOR (row>>4)&3 on the 2-byte transposing writes and the eight 8-byte-pair MFMA operand reads
# speedup vs baseline: 1.0507x; 1.0023x over previous
.LBB0_976:
	s_or_b64 exec, exec, s[4:5]
	s_add_u32 s58, s84, 0x9b00000
	s_addc_u32 s59, s85, 0
	v_mov_b32_e32 v0, v191
	s_and_b64 vcc, exec, s[0:1]
	s_waitcnt lgkmcnt(0)
	s_barrier
	s_cbranch_vccz .LBB0_993
	v_ashrrev_i32_e32 v1, 6, v0
	v_lshlrev_b32_e32 v3, 3, v0
	v_and_b32_e32 v3, 0x78, v3
	v_bfe_u32 v5, v0, 4, 2
	v_lshlrev_b32_e32 v4, 3, v1
	v_ashrrev_i32_e32 v9, 7, v0
	v_mov_b32_e32 v97, 0
	v_lshlrev_b32_e32 v96, 1, v3
	v_and_b32_e32 v100, 15, v0
	v_bfi_b32 v109, -16, v4, v0
	v_lshlrev_b32_e32 v4, 2, v5
	v_lshlrev_b32_e32 v111, 4, v9
	v_lshl_add_u64 v[98:99], s[14:15], 0, v[96:97]
	v_lshlrev_b32_e32 v8, 3, v5
	v_lshlrev_b32_e32 v96, 4, v5
	v_or_b32_e32 v135, v111, v100
	v_cmp_eq_u32_e64 s[12:13], 0, v5
	v_or_b32_e32 v5, 2, v4
	v_cmp_gt_i32_e64 s[20:21], v5, v135
	v_or_b32_e32 v5, 3, v4
	v_cmp_gt_i32_e64 s[22:23], v5, v135
	v_or_b32_e32 v5, 16, v4
	v_cmp_gt_i32_e64 s[24:25], v5, v135
	v_or_b32_e32 v5, 17, v4
	v_lshlrev_b32_e32 v2, 4, v0
	v_lshlrev_b32_e32 v10, 2, v0
	v_cmp_gt_i32_e64 s[26:27], v5, v135
	v_or_b32_e32 v5, 18, v4
	v_ashrrev_i32_e32 v101, 3, v0
	v_and_b32_e32 v2, 0x70, v2
	v_lshl_add_u64 v[102:103], s[28:29], 0, v[96:97]
	v_and_b32_e32 v6, 0x1fc, v10
	v_mov_b32_e32 v7, v97
	v_cmp_gt_i32_e64 s[28:29], v5, v135
	v_or_b32_e32 v5, 19, v4
	v_lshl_add_u64 v[104:105], s[30:31], 0, v[6:7]
	v_add_u32_e32 v128, 16, v6
	v_max_i32_e32 v6, 1, v101
	s_movk_i32 s3, 0x210
	v_lshlrev_b32_e32 v12, 2, v2
	v_cmp_gt_i32_e64 s[30:31], v5, v135
	v_or_b32_e32 v5, 32, v4
	v_mul_lo_u32 v11, v101, s3
	v_mul_lo_u32 v6, v6, s3
	v_add_u32_e32 v130, 16, v12
	s_movk_i32 s0, 0xfdf0
	v_cmp_gt_i32_e64 s[34:35], v5, v135
	v_or_b32_e32 v5, 33, v4
	v_add_u32_e32 v11, 16, v11
	v_add3_u32 v131, v130, v6, s0
	v_lshlrev_b32_e32 v6, 8, v101
	v_cmp_gt_i32_e64 s[36:37], v5, v135
	v_or_b32_e32 v5, 34, v4
	s_add_u32 s62, s84, 0x19b00000
	v_add_u32_e32 v129, v11, v12
	v_sub_u32_e32 v6, v11, v6
	v_lshlrev_b32_e32 v11, 1, v2
	s_movk_i32 s16, 0x110
	v_cmp_gt_i32_e64 s[38:39], v5, v135
	v_or_b32_e32 v5, 35, v4
	s_addc_u32 s63, s85, 0
	v_add_u32_e32 v132, v6, v11
	s_add_i32 s0, 16, 0x12800
	v_mul_lo_u32 v6, v101, s16
	s_add_i32 s1, 16, 0x16c00
	v_cmp_gt_i32_e64 s[40:41], v5, v135
	v_or_b32_e32 v5, 48, v4
	v_add3_u32 v133, s0, v6, v11
	v_add3_u32 v134, s1, v6, v11
	v_and_b32_e32 v1, 1, v1
	v_mul_lo_u32 v6, v135, s16
	v_cmp_gt_i32_e64 s[42:43], v5, v135
	v_or_b32_e32 v5, 49, v4
	v_add3_u32 v136, s0, v6, v96
	v_add3_u32 v137, s1, v6, v96
	v_lshlrev_b32_e32 v6, 6, v1
	v_cmp_lt_i32_e64 s[0:1], v197, v195
	v_lshl_add_u32 v140, v135, 3, 16
	v_cmp_gt_i32_e64 s[44:45], v5, v135
	v_or_b32_e32 v5, 50, v4
	v_ashrrev_i32_e32 v107, 4, v0
	v_and_b32_e32 v7, 0xffffff0, v101
	v_add_u32_e32 v11, 16, v96
	v_or_b32_e32 v12, v6, v100
	v_cndmask_b32_e64 v13, v193, v197, s[0:1]
	v_cmp_lt_i32_e64 s[0:1], v206, v195
	v_lshl_add_u32 v141, v1, 2, v140
	v_or_b32_e32 v6, v6, v4
	v_or_b32_e32 v1, 15, v101
	v_cmp_gt_i32_e64 s[46:47], v5, v135
	v_or_b32_e32 v5, 51, v4
	v_add_u32_e32 v113, 16, v10
	v_lshl_add_u32 v10, v107, 1, 16
	v_sub_u32_e32 v8, v11, v8
	v_lshlrev_b32_e32 v138, 2, v13
	v_cndmask_b32_e64 v13, v193, v206, s[0:1]
	v_and_b32_e32 v106, 64, v0
	v_mul_lo_u32 v0, v7, s3
	v_mul_lo_u32 v1, v1, s3
	v_mul_u32_u24_e32 v3, 0x90, v3
	v_mad_u32_u24 v142, v100, s16, v11
	v_cmp_gt_i32_e64 s[48:49], v5, v135
	v_mul_u32_u24_e32 v5, 0x90, v12
	v_lshlrev_b32_e32 v96, 2, v6
	s_mov_b32 s69, 0
	v_cmp_lt_i32_e32 vcc, 0, v9
	v_cmp_lt_i32_e64 s[4:5], 1, v9
	v_cmp_lt_i32_e64 s[6:7], 2, v9
	v_cmp_lt_i32_e64 s[8:9], 3, v9
	v_cmp_lt_i32_e64 s[10:11], 0, v101
	v_lshlrev_b32_e32 v139, 2, v13
	v_or_b32_e32 v108, 16, v106
	v_or_b32_e32 v110, 32, v106
	v_or_b32_e32 v112, 48, v106
	v_cmp_lt_i32_e64 s[14:15], -1, v9
	v_add_u32_e32 v143, 0xe400, v142
	v_cmp_gt_i32_e64 s[16:17], v4, v135
	v_cmp_lt_i32_e64 s[18:19], v4, v135
	v_lshl_add_u64 v[114:115], s[60:61], 0, v[96:97]
	s_lshl_b32 s55, s2, 6
	s_lshl_b32 s70, s86, 6
	v_lshlrev_b32_e32 v96, 1, v2
	s_mov_b32 s71, 0x10000
	v_lshlrev_b32_e32 v116, 1, v4
	v_add_u32_e32 v144, v128, v0
	v_add_u32_e32 v145, v128, v1
	v_add_u32_e32 v146, v10, v3
	v_mov_b32_e32 v147, 0x358637bd
	s_mov_b32 s72, 0x800000
	v_lshlrev_b32_e32 v118, 1, v6
	v_add_u32_e32 v148, v8, v5
	v_bfe_u32 v184, v191, 1, 2
	v_bfe_u32 v185, v191, 7, 2
	v_xor_b32_e32 v186, v185, v184
	v_sub_u32_e32 v186, v186, v185
	v_lshl_add_u32 v146, v186, 4, v146
	v_bfe_u32 v184, v191, 5, 1
	v_lshlrev_b32_e32 v184, 5, v184
	v_sub_u32_e32 v184, v148, v184
	v_add_u32_e32 v187, 16, v184
	s_mov_b32 s73, s97
	s_and_b32 s0, s73, 0xffffc000
	s_and_b32 s1, s55, 0x3fc0
	s_or_b32 s74, s0, s1
	s_lshr_b32 s0, s2, 1
	s_and_b32 s0, s0, 0x380
	s_lshl_b32 s60, s0, 2
	s_mov_b32 s61, s69
	s_lshl_b32 s68, s0, 1
	v_add_u32_e32 v2, s74, v111
	v_ashrrev_i32_e32 v3, 31, v2
	v_or_b32_e32 v8, 1, v2
	v_or_b32_e32 v10, 2, v2
	v_or_b32_e32 v12, 3, v2
	v_or_b32_e32 v14, 4, v2
	v_or_b32_e32 v16, 5, v2
	v_or_b32_e32 v18, 6, v2
	v_or_b32_e32 v20, 7, v2
	v_lshl_add_u64 v[4:5], v[104:105], 0, s[60:61]
	v_lshlrev_b64 v[6:7], 12, v[2:3]
	v_ashrrev_i32_e32 v9, 31, v8
	v_ashrrev_i32_e32 v11, 31, v10
	v_ashrrev_i32_e32 v13, 31, v12
	v_ashrrev_i32_e32 v15, 31, v14
	v_ashrrev_i32_e32 v17, 31, v16
	v_ashrrev_i32_e32 v19, 31, v18
	v_ashrrev_i32_e32 v21, 31, v20
	v_lshl_add_u64 v[6:7], v[4:5], 0, v[6:7]
	v_lshlrev_b64 v[8:9], 12, v[8:9]
	v_lshlrev_b64 v[10:11], 12, v[10:11]
	v_lshlrev_b64 v[12:13], 12, v[12:13]
	v_lshlrev_b64 v[14:15], 12, v[14:15]
	v_lshlrev_b64 v[16:17], 12, v[16:17]
	v_lshlrev_b64 v[18:19], 12, v[18:19]
	v_lshlrev_b64 v[20:21], 12, v[20:21]
	v_lshl_add_u64 v[8:9], v[4:5], 0, v[8:9]
	v_lshl_add_u64 v[10:11], v[4:5], 0, v[10:11]
	v_lshl_add_u64 v[12:13], v[4:5], 0, v[12:13]
	v_lshl_add_u64 v[14:15], v[4:5], 0, v[14:15]
	v_lshl_add_u64 v[16:17], v[4:5], 0, v[16:17]
	v_lshl_add_u64 v[18:19], v[4:5], 0, v[18:19]
	v_lshl_add_u64 v[20:21], v[4:5], 0, v[20:21]
	global_load_dword v216, v[6:7], off
	global_load_dword v217, v[8:9], off
	global_load_dword v218, v[10:11], off
	global_load_dword v219, v[12:13], off
	global_load_dword v220, v[14:15], off
	global_load_dword v221, v[16:17], off
	global_load_dword v222, v[18:19], off
	global_load_dword v223, v[20:21], off
	v_or_b32_e32 v6, 8, v2
	v_ashrrev_i32_e32 v7, 31, v6
	v_or_b32_e32 v8, 9, v2
	v_or_b32_e32 v10, 10, v2
	v_or_b32_e32 v12, 11, v2
	v_or_b32_e32 v14, 12, v2
	v_or_b32_e32 v16, 13, v2
	v_or_b32_e32 v18, 14, v2
	v_or_b32_e32 v2, 15, v2
	v_lshlrev_b64 v[6:7], 12, v[6:7]
	v_ashrrev_i32_e32 v9, 31, v8
	v_ashrrev_i32_e32 v11, 31, v10
	v_ashrrev_i32_e32 v13, 31, v12
	v_ashrrev_i32_e32 v15, 31, v14
	v_ashrrev_i32_e32 v17, 31, v16
	v_ashrrev_i32_e32 v19, 31, v18
	v_ashrrev_i32_e32 v3, 31, v2
	v_lshl_add_u64 v[6:7], v[4:5], 0, v[6:7]
	v_lshlrev_b64 v[8:9], 12, v[8:9]
	v_lshlrev_b64 v[10:11], 12, v[10:11]
	v_lshlrev_b64 v[12:13], 12, v[12:13]
	v_lshlrev_b64 v[14:15], 12, v[14:15]
	v_lshlrev_b64 v[16:17], 12, v[16:17]
	v_lshlrev_b64 v[18:19], 12, v[18:19]
	v_lshlrev_b64 v[2:3], 12, v[2:3]
	v_lshl_add_u64 v[8:9], v[4:5], 0, v[8:9]
	v_lshl_add_u64 v[10:11], v[4:5], 0, v[10:11]
	v_lshl_add_u64 v[12:13], v[4:5], 0, v[12:13]
	v_lshl_add_u64 v[14:15], v[4:5], 0, v[14:15]
	v_lshl_add_u64 v[16:17], v[4:5], 0, v[16:17]
	v_lshl_add_u64 v[18:19], v[4:5], 0, v[18:19]
	v_lshl_add_u64 v[2:3], v[4:5], 0, v[2:3]
	global_load_dword v224, v[6:7], off
	global_load_dword v225, v[8:9], off
	global_load_dword v226, v[10:11], off
	global_load_dword v227, v[12:13], off
	global_load_dword v228, v[14:15], off
	global_load_dword v229, v[16:17], off
	global_load_dword v230, v[18:19], off
	global_load_dword v231, v[2:3], off
	v_add_u32_e32 v0, s74, v101
	v_ashrrev_i32_e32 v1, 31, v0
	v_lshlrev_b64 v[0:1], 11, v[0:1]
	v_lshl_add_u64 v[0:1], s[58:59], 0, v[0:1]
	v_lshl_add_u64 v[0:1], v[0:1], 0, s[68:69]
	v_lshl_add_u64 v[0:1], v[0:1], 0, v[96:97]
	global_load_dwordx4 v[232:235], v[0:1], off offset:16
	global_load_dwordx4 v[236:239], v[0:1], off
	v_add_u32_e32 v0, s74, v107
	v_ashrrev_i32_e32 v1, 31, v0
	v_lshl_add_u64 v[2:3], v[98:99], 0, s[68:69]
	v_lshlrev_b64 v[0:1], 11, v[0:1]
	v_lshl_add_u64 v[0:1], v[2:3], 0, v[0:1]
	v_add_co_u32_e64 v2, s[98:99], s71, v0
	s_nop 0
	s_nop 0
	v_addc_co_u32_e64 v3, s[98:99], 0, v1, s[98:99]
	global_load_dwordx4 v[240:243], v[0:1], off
	global_load_dwordx4 v[244:247], v[2:3], off
	s_waitcnt vmcnt(0)
	s_branch .LBB0_979

.LBB0_987:
	s_or_b64 exec, exec, s[0:1]
	s_waitcnt lgkmcnt(2)
	v_mov_b32_e32 v82, v97
	v_mov_b32_e32 v83, v97
	v_mov_b32_e32 v80, v97
	v_mov_b32_e32 v81, v97
	v_mov_b64_e32 v[94:95], v[82:83]
	v_mov_b64_e32 v[90:91], v[82:83]
	v_mov_b64_e32 v[86:87], v[82:83]
	v_add_u32_e32 v166, 0x8800, v148
	v_add_u32_e32 v165, 0x9000, v187
	v_add_u32_e32 v164, 0x9800, v148
	v_add_u32_e32 v162, 0xa000, v187
	v_mov_b64_e32 v[92:93], v[80:81]
	v_mov_b64_e32 v[88:89], v[80:81]
	v_mov_b64_e32 v[84:85], v[80:81]
	s_and_saveexec_b64 s[0:1], s[14:15]
	s_cbranch_execz .LBB0_989
	ds_read2_b64 v[80:83], v166 offset1:4
	v_cvt_pk_bf16_f32 v168, v149, v119
	v_cvt_pk_bf16_f32 v169, v150, v151
	v_cvt_pk_bf16_f32 v170, v155, v156
	v_cvt_pk_bf16_f32 v171, v157, v158
	s_waitcnt lgkmcnt(0)
	s_nop 0
	v_mfma_f32_16x16x32_bf16 v[84:87], v[80:83], v[168:171], 0
	ds_read2_b64 v[80:83], v165 offset0:32 offset1:36
	s_waitcnt lgkmcnt(0)
	v_mfma_f32_16x16x32_bf16 v[88:91], v[80:83], v[168:171], 0
	ds_read2_b64 v[80:83], v164 offset0:68 offset1:64
	s_waitcnt lgkmcnt(0)
	v_mfma_f32_16x16x32_bf16 v[92:95], v[80:83], v[168:171], 0
	ds_read2_b64 v[80:83], v162 offset0:100 offset1:96
	s_waitcnt lgkmcnt(0)
	v_mfma_f32_16x16x32_bf16 v[80:83], v[80:83], v[168:171], 0
.LBB0_989:
	s_or_b64 exec, exec, s[0:1]
	s_and_saveexec_b64 s[0:1], s[4:5]
	s_cbranch_execz .LBB0_991
	v_cvt_pk_bf16_f32 v151, v153, v154
	ds_read2_b64 v[154:157], v165 offset0:40 offset1:44
	v_cvt_pk_bf16_f32 v150, v117, v152
	v_cvt_pk_bf16_f32 v152, v159, v160
	v_cvt_pk_bf16_f32 v153, v161, v163
	ds_read2_b64 v[166:169], v166 offset0:8 offset1:12
	s_waitcnt lgkmcnt(1)
	v_mfma_f32_16x16x32_bf16 v[88:91], v[154:157], v[150:153], v[88:91]
	ds_read2_b64 v[154:157], v164 offset0:76 offset1:72
	s_waitcnt lgkmcnt(1)
	v_mfma_f32_16x16x32_bf16 v[84:87], v[166:169], v[150:153], v[84:87]
	s_waitcnt lgkmcnt(0)
	v_mfma_f32_16x16x32_bf16 v[92:95], v[154:157], v[150:153], v[92:95]
	ds_read2_b64 v[154:157], v162 offset0:108 offset1:104
	s_waitcnt lgkmcnt(0)
	v_mfma_f32_16x16x32_bf16 v[80:83], v[154:157], v[150:153], v[80:83]
